# FFN gate/up GEMM K-loop: 12 of 16 LDS-DMA loads per iteration switched to SGPR-base addressing (no per-load 64-bit VALU add)
# speedup vs baseline: 1.0158x; 1.0158x over previous
.LBB0_920:
	s_add_u32 s28, s46, 0xfff80080
	s_addc_u32 s29, s47, -1
	s_add_i32 s91, 0, 0x10000
	s_cmp_eq_u32 s90, 28
	s_cselect_b32 s49, s27, s29
	s_cselect_b32 s48, s86, s28
	s_cselect_b32 s29, s23, s89
	s_cselect_b32 s28, s87, s88
	s_add_i32 s94, 0, 0x14000
	v_add_u32_e32 v156, s91, v141
	v_add_u32_e32 v172, s94, v141
	ds_read_b128 v[144:147], v156
	ds_read_b128 v[148:151], v156 offset:1024
	ds_read_b128 v[152:155], v156 offset:2048
	ds_read_b128 v[156:159], v156 offset:3072
	ds_read_b128 v[160:163], v172
	ds_read_b128 v[164:167], v172 offset:1024
	ds_read_b128 v[168:171], v172 offset:2048
	ds_read_b128 v[172:175], v172 offset:3072
	s_add_i32 m0, s45, 0xc000
	ds_read_b128 v[176:179], v143
	ds_read_b128 v[180:183], v143 offset:1024
	ds_read_b128 v[184:187], v143 offset:2048
	ds_read_b128 v[188:191], v143 offset:3072
	ds_read_b128 v[192:195], v143 offset:4096
	ds_read_b128 v[196:199], v143 offset:5120
	ds_read_b128 v[200:203], v143 offset:6144
	ds_read_b128 v[204:207], v143 offset:7168
	global_load_lds_dwordx4 v136, s[46:47]
	s_add_i32 m0, s45, 0xe000
	s_nop 0
	global_load_lds_dwordx4 v138, s[46:47]
	s_waitcnt vmcnt(8)
	s_waitcnt lgkmcnt(0)
	s_barrier
	s_setprio 1
	s_waitcnt lgkmcnt(0)
	v_mfma_f32_16x16x32_bf16 v[126:129], v[144:147], v[176:179], v[126:129]
	v_mfma_f32_16x16x32_bf16 v[118:121], v[152:155], v[176:179], v[118:121]
	v_mfma_f32_16x16x32_bf16 v[110:113], v[144:147], v[184:187], v[110:113]
	v_mfma_f32_16x16x32_bf16 v[102:105], v[152:155], v[184:187], v[102:105]
	v_mfma_f32_16x16x32_bf16 v[94:97], v[144:147], v[192:195], v[94:97]
	v_mfma_f32_16x16x32_bf16 v[86:89], v[152:155], v[192:195], v[86:89]
	v_mfma_f32_16x16x32_bf16 v[78:81], v[144:147], v[200:203], v[78:81]
	v_mfma_f32_16x16x32_bf16 v[70:73], v[152:155], v[200:203], v[70:73]
	v_mfma_f32_16x16x32_bf16 v[126:129], v[148:151], v[180:183], v[126:129]
	v_mfma_f32_16x16x32_bf16 v[118:121], v[156:159], v[180:183], v[118:121]
	v_mfma_f32_16x16x32_bf16 v[110:113], v[148:151], v[188:191], v[110:113]
	v_mfma_f32_16x16x32_bf16 v[102:105], v[156:159], v[188:191], v[102:105]
	v_mfma_f32_16x16x32_bf16 v[94:97], v[148:151], v[196:199], v[94:97]
	v_mfma_f32_16x16x32_bf16 v[86:89], v[156:159], v[196:199], v[86:89]
	v_mfma_f32_16x16x32_bf16 v[78:81], v[148:151], v[204:207], v[78:81]
	v_mfma_f32_16x16x32_bf16 v[70:73], v[156:159], v[204:207], v[70:73]
	s_setprio 0
	s_setprio 1
	v_mfma_f32_16x16x32_bf16 v[122:125], v[160:163], v[176:179], v[122:125]
	v_mfma_f32_16x16x32_bf16 v[114:117], v[168:171], v[176:179], v[114:117]
	v_mfma_f32_16x16x32_bf16 v[106:109], v[160:163], v[184:187], v[106:109]
	v_mfma_f32_16x16x32_bf16 v[98:101], v[168:171], v[184:187], v[98:101]
	v_mfma_f32_16x16x32_bf16 v[90:93], v[160:163], v[192:195], v[90:93]
	v_mfma_f32_16x16x32_bf16 v[82:85], v[168:171], v[192:195], v[82:85]
	v_mfma_f32_16x16x32_bf16 v[74:77], v[160:163], v[200:203], v[74:77]
	v_mfma_f32_16x16x32_bf16 v[66:69], v[168:171], v[200:203], v[66:69]
	v_mfma_f32_16x16x32_bf16 v[122:125], v[164:167], v[180:183], v[122:125]
	v_mfma_f32_16x16x32_bf16 v[114:117], v[172:175], v[180:183], v[114:117]
	v_mfma_f32_16x16x32_bf16 v[106:109], v[164:167], v[188:191], v[106:109]
	v_mfma_f32_16x16x32_bf16 v[98:101], v[172:175], v[188:191], v[98:101]
	v_mfma_f32_16x16x32_bf16 v[90:93], v[164:167], v[196:199], v[90:93]
	v_mfma_f32_16x16x32_bf16 v[82:85], v[172:175], v[196:199], v[82:85]
	v_mfma_f32_16x16x32_bf16 v[74:77], v[164:167], v[204:207], v[74:77]
	v_mfma_f32_16x16x32_bf16 v[66:69], v[172:175], v[204:207], v[66:69]
	s_setprio 0
	s_barrier
	s_add_i32 s91, s91, s37
	s_mov_b32 m0, s91
	ds_read_b128 v[176:179], v143 offset:16384
	ds_read_b128 v[180:183], v143 offset:17408
	ds_read_b128 v[184:187], v143 offset:18432
	ds_read_b128 v[188:191], v143 offset:19456
	ds_read_b128 v[192:195], v143 offset:20480
	ds_read_b128 v[196:199], v143 offset:21504
	ds_read_b128 v[200:203], v143 offset:22528
	ds_read_b128 v[204:207], v143 offset:23552
	global_load_lds_dwordx4 v16, s[28:29]
	s_add_i32 m0, s91, 0x2000
	s_add_u32 s92, s28, 0x80000
	s_addc_u32 s93, s29, 0
	s_add_i32 s91, s94, s37
	global_load_lds_dwordx4 v130, s[28:29]
	s_mov_b32 m0, s91
	v_lshl_add_u64 v[228:229], s[48:49], 0, v[132:133]
	global_load_lds_dwordx4 v16, s[92:93]
	s_add_i32 m0, s91, 0x2000
	s_nop 0
	global_load_lds_dwordx4 v130, s[92:93]
	v_lshl_add_u64 v[226:227], s[48:49], 0, v[134:135]
	s_mov_b32 m0, s45
	s_nop 0
	global_load_lds_dwordx4 v[226:227], off
	s_mov_b32 m0, s53
	s_nop 0
	global_load_lds_dwordx4 v[228:229], off
	s_waitcnt vmcnt(8)
	s_waitcnt lgkmcnt(0)
	s_barrier
	s_setprio 1
	s_waitcnt lgkmcnt(0)
	v_mfma_f32_16x16x32_bf16 v[62:65], v[144:147], v[176:179], v[62:65]
	v_mfma_f32_16x16x32_bf16 v[54:57], v[152:155], v[176:179], v[54:57]
	v_mfma_f32_16x16x32_bf16 v[46:49], v[144:147], v[184:187], v[46:49]
	v_mfma_f32_16x16x32_bf16 v[38:41], v[152:155], v[184:187], v[38:41]
	v_mfma_f32_16x16x32_bf16 v[30:33], v[144:147], v[192:195], v[30:33]
	v_mfma_f32_16x16x32_bf16 v[22:25], v[152:155], v[192:195], v[22:25]
	v_mfma_f32_16x16x32_bf16 v[12:15], v[144:147], v[200:203], v[12:15]
	v_mfma_f32_16x16x32_bf16 v[4:7], v[152:155], v[200:203], v[4:7]
	v_mfma_f32_16x16x32_bf16 v[62:65], v[148:151], v[180:183], v[62:65]
	v_mfma_f32_16x16x32_bf16 v[54:57], v[156:159], v[180:183], v[54:57]
	v_mfma_f32_16x16x32_bf16 v[46:49], v[148:151], v[188:191], v[46:49]
	v_mfma_f32_16x16x32_bf16 v[38:41], v[156:159], v[188:191], v[38:41]
	v_mfma_f32_16x16x32_bf16 v[30:33], v[148:151], v[196:199], v[30:33]
	v_mfma_f32_16x16x32_bf16 v[22:25], v[156:159], v[196:199], v[22:25]
	v_mfma_f32_16x16x32_bf16 v[12:15], v[148:151], v[204:207], v[12:15]
	v_mfma_f32_16x16x32_bf16 v[4:7], v[156:159], v[204:207], v[4:7]
	s_setprio 0
	s_setprio 1
	v_mfma_f32_16x16x32_bf16 v[58:61], v[160:163], v[176:179], v[58:61]
	v_mfma_f32_16x16x32_bf16 v[50:53], v[168:171], v[176:179], v[50:53]
	v_mfma_f32_16x16x32_bf16 v[42:45], v[160:163], v[184:187], v[42:45]
	v_mfma_f32_16x16x32_bf16 v[34:37], v[168:171], v[184:187], v[34:37]
	v_mfma_f32_16x16x32_bf16 v[26:29], v[160:163], v[192:195], v[26:29]
	v_mfma_f32_16x16x32_bf16 v[18:21], v[168:171], v[192:195], v[18:21]
	v_mfma_f32_16x16x32_bf16 v[8:11], v[160:163], v[200:203], v[8:11]
	v_mfma_f32_16x16x32_bf16 v[0:3], v[168:171], v[200:203], v[0:3]
	v_mfma_f32_16x16x32_bf16 v[58:61], v[164:167], v[180:183], v[58:61]
	v_mfma_f32_16x16x32_bf16 v[50:53], v[172:175], v[180:183], v[50:53]
	v_mfma_f32_16x16x32_bf16 v[42:45], v[164:167], v[188:191], v[42:45]
	v_mfma_f32_16x16x32_bf16 v[34:37], v[172:175], v[188:191], v[34:37]
	v_mfma_f32_16x16x32_bf16 v[26:29], v[164:167], v[196:199], v[26:29]
	v_mfma_f32_16x16x32_bf16 v[18:21], v[172:175], v[196:199], v[18:21]
	v_mfma_f32_16x16x32_bf16 v[8:11], v[164:167], v[204:207], v[8:11]
	v_mfma_f32_16x16x32_bf16 v[0:3], v[172:175], v[204:207], v[0:3]
	s_setprio 0
	s_barrier
	s_add_i32 s91, 0, 0x18000
	s_add_i32 s92, 0, 0x1c000
	v_add_u32_e32 v156, s91, v141
	v_add_u32_e32 v172, s92, v141
	ds_read_b128 v[144:147], v156
	ds_read_b128 v[148:151], v156 offset:1024
	ds_read_b128 v[152:155], v156 offset:2048
	ds_read_b128 v[156:159], v156 offset:3072
	ds_read_b128 v[160:163], v172
	ds_read_b128 v[164:167], v172 offset:1024
	ds_read_b128 v[168:171], v172 offset:2048
	ds_read_b128 v[172:175], v172 offset:3072
	s_add_u32 s48, s48, 0x80000
	s_addc_u32 s49, s49, 0
	s_mov_b32 m0, s57
	ds_read_b128 v[176:179], v143 offset:32768
	ds_read_b128 v[180:183], v143 offset:33792
	ds_read_b128 v[184:187], v143 offset:34816
	ds_read_b128 v[188:191], v143 offset:35840
	ds_read_b128 v[192:195], v143 offset:36864
	ds_read_b128 v[196:199], v143 offset:37888
	ds_read_b128 v[200:203], v143 offset:38912
	ds_read_b128 v[204:207], v143 offset:39936
	global_load_lds_dwordx4 v134, s[48:49]
	s_mov_b32 m0, s58
	s_nop 0
	global_load_lds_dwordx4 v132, s[48:49]
	s_waitcnt vmcnt(8)
	s_waitcnt lgkmcnt(0)
	s_barrier
	s_setprio 1
	s_waitcnt lgkmcnt(0)
	v_mfma_f32_16x16x32_bf16 v[126:129], v[144:147], v[176:179], v[126:129]
	v_mfma_f32_16x16x32_bf16 v[118:121], v[152:155], v[176:179], v[118:121]
	v_mfma_f32_16x16x32_bf16 v[110:113], v[144:147], v[184:187], v[110:113]
	v_mfma_f32_16x16x32_bf16 v[102:105], v[152:155], v[184:187], v[102:105]
	v_mfma_f32_16x16x32_bf16 v[94:97], v[144:147], v[192:195], v[94:97]
	v_mfma_f32_16x16x32_bf16 v[86:89], v[152:155], v[192:195], v[86:89]
	v_mfma_f32_16x16x32_bf16 v[78:81], v[144:147], v[200:203], v[78:81]
	v_mfma_f32_16x16x32_bf16 v[70:73], v[152:155], v[200:203], v[70:73]
	v_mfma_f32_16x16x32_bf16 v[126:129], v[148:151], v[180:183], v[126:129]
	v_mfma_f32_16x16x32_bf16 v[118:121], v[156:159], v[180:183], v[118:121]
	v_mfma_f32_16x16x32_bf16 v[110:113], v[148:151], v[188:191], v[110:113]
	v_mfma_f32_16x16x32_bf16 v[102:105], v[156:159], v[188:191], v[102:105]
	v_mfma_f32_16x16x32_bf16 v[94:97], v[148:151], v[196:199], v[94:97]
	v_mfma_f32_16x16x32_bf16 v[86:89], v[156:159], v[196:199], v[86:89]
	v_mfma_f32_16x16x32_bf16 v[78:81], v[148:151], v[204:207], v[78:81]
	v_mfma_f32_16x16x32_bf16 v[70:73], v[156:159], v[204:207], v[70:73]
	s_setprio 0
	s_setprio 1
	v_mfma_f32_16x16x32_bf16 v[122:125], v[160:163], v[176:179], v[122:125]
	v_mfma_f32_16x16x32_bf16 v[114:117], v[168:171], v[176:179], v[114:117]
	v_mfma_f32_16x16x32_bf16 v[106:109], v[160:163], v[184:187], v[106:109]
	v_mfma_f32_16x16x32_bf16 v[98:101], v[168:171], v[184:187], v[98:101]
	v_mfma_f32_16x16x32_bf16 v[90:93], v[160:163], v[192:195], v[90:93]
	v_mfma_f32_16x16x32_bf16 v[82:85], v[168:171], v[192:195], v[82:85]
	v_mfma_f32_16x16x32_bf16 v[74:77], v[160:163], v[200:203], v[74:77]
	v_mfma_f32_16x16x32_bf16 v[66:69], v[168:171], v[200:203], v[66:69]
	v_mfma_f32_16x16x32_bf16 v[122:125], v[164:167], v[180:183], v[122:125]
	v_mfma_f32_16x16x32_bf16 v[114:117], v[172:175], v[180:183], v[114:117]
	v_mfma_f32_16x16x32_bf16 v[106:109], v[164:167], v[188:191], v[106:109]
	v_mfma_f32_16x16x32_bf16 v[98:101], v[172:175], v[188:191], v[98:101]
	v_mfma_f32_16x16x32_bf16 v[90:93], v[164:167], v[196:199], v[90:93]
	v_mfma_f32_16x16x32_bf16 v[82:85], v[172:175], v[196:199], v[82:85]
	v_mfma_f32_16x16x32_bf16 v[74:77], v[164:167], v[204:207], v[74:77]
	v_mfma_f32_16x16x32_bf16 v[66:69], v[172:175], v[204:207], v[66:69]
	s_setprio 0
	s_barrier
	s_add_i32 s48, s91, s37
	s_add_u32 s28, s28, 0x80
	s_addc_u32 s29, s29, 0
	s_mov_b32 m0, s48
	ds_read_b128 v[176:179], v143 offset:49152
	ds_read_b128 v[180:183], v143 offset:50176
	ds_read_b128 v[184:187], v143 offset:51200
	ds_read_b128 v[188:191], v143 offset:52224
	ds_read_b128 v[192:195], v143 offset:53248
	ds_read_b128 v[196:199], v143 offset:54272
	ds_read_b128 v[200:203], v143 offset:55296
	ds_read_b128 v[204:207], v143 offset:56320
	global_load_lds_dwordx4 v16, s[28:29]
	s_add_i32 m0, s48, 0x2000
	s_add_i32 s48, s92, s37
	global_load_lds_dwordx4 v130, s[28:29]
	s_add_u32 s28, s28, 0x80000
	s_addc_u32 s29, s29, 0
	s_mov_b32 m0, s48
	s_nop 0
	global_load_lds_dwordx4 v16, s[28:29]
	s_add_i32 m0, s48, 0x2000
	s_nop 0
	global_load_lds_dwordx4 v130, s[28:29]
	v_lshl_add_u64 v[216:217], v[226:227], 0, s[34:35]
	s_mov_b32 m0, s59
	s_nop 0
	global_load_lds_dwordx4 v[216:217], off
	v_lshl_add_u64 v[216:217], v[228:229], 0, s[34:35]
	s_mov_b32 m0, s83
	s_nop 0
	global_load_lds_dwordx4 v[216:217], off
	s_waitcnt vmcnt(8)
	s_waitcnt lgkmcnt(0)
	s_barrier
	s_setprio 1
	s_waitcnt lgkmcnt(0)
	v_mfma_f32_16x16x32_bf16 v[62:65], v[144:147], v[176:179], v[62:65]
	v_mfma_f32_16x16x32_bf16 v[54:57], v[152:155], v[176:179], v[54:57]
	v_mfma_f32_16x16x32_bf16 v[46:49], v[144:147], v[184:187], v[46:49]
	v_mfma_f32_16x16x32_bf16 v[38:41], v[152:155], v[184:187], v[38:41]
	v_mfma_f32_16x16x32_bf16 v[30:33], v[144:147], v[192:195], v[30:33]
	v_mfma_f32_16x16x32_bf16 v[22:25], v[152:155], v[192:195], v[22:25]
	v_mfma_f32_16x16x32_bf16 v[12:15], v[144:147], v[200:203], v[12:15]
	v_mfma_f32_16x16x32_bf16 v[4:7], v[152:155], v[200:203], v[4:7]
	v_mfma_f32_16x16x32_bf16 v[62:65], v[148:151], v[180:183], v[62:65]
	v_mfma_f32_16x16x32_bf16 v[54:57], v[156:159], v[180:183], v[54:57]
	v_mfma_f32_16x16x32_bf16 v[46:49], v[148:151], v[188:191], v[46:49]
	v_mfma_f32_16x16x32_bf16 v[38:41], v[156:159], v[188:191], v[38:41]
	v_mfma_f32_16x16x32_bf16 v[30:33], v[148:151], v[196:199], v[30:33]
	v_mfma_f32_16x16x32_bf16 v[22:25], v[156:159], v[196:199], v[22:25]
	v_mfma_f32_16x16x32_bf16 v[12:15], v[148:151], v[204:207], v[12:15]
	v_mfma_f32_16x16x32_bf16 v[4:7], v[156:159], v[204:207], v[4:7]
	s_setprio 0
	s_setprio 1
	v_mfma_f32_16x16x32_bf16 v[58:61], v[160:163], v[176:179], v[58:61]
	v_mfma_f32_16x16x32_bf16 v[50:53], v[168:171], v[176:179], v[50:53]
	v_mfma_f32_16x16x32_bf16 v[42:45], v[160:163], v[184:187], v[42:45]
	v_mfma_f32_16x16x32_bf16 v[34:37], v[168:171], v[184:187], v[34:37]
	v_mfma_f32_16x16x32_bf16 v[26:29], v[160:163], v[192:195], v[26:29]
	v_mfma_f32_16x16x32_bf16 v[18:21], v[168:171], v[192:195], v[18:21]
	v_mfma_f32_16x16x32_bf16 v[8:11], v[160:163], v[200:203], v[8:11]
	v_mfma_f32_16x16x32_bf16 v[0:3], v[168:171], v[200:203], v[0:3]
	v_mfma_f32_16x16x32_bf16 v[58:61], v[164:167], v[180:183], v[58:61]
	v_mfma_f32_16x16x32_bf16 v[50:53], v[172:175], v[180:183], v[50:53]
	v_mfma_f32_16x16x32_bf16 v[42:45], v[164:167], v[188:191], v[42:45]
	v_mfma_f32_16x16x32_bf16 v[34:37], v[172:175], v[188:191], v[34:37]
	v_mfma_f32_16x16x32_bf16 v[26:29], v[164:167], v[196:199], v[26:29]
	v_mfma_f32_16x16x32_bf16 v[18:21], v[172:175], v[196:199], v[18:21]
	v_mfma_f32_16x16x32_bf16 v[8:11], v[164:167], v[204:207], v[8:11]
	v_mfma_f32_16x16x32_bf16 v[0:3], v[172:175], v[204:207], v[0:3]
	s_setprio 0
	s_barrier
	s_add_i32 s90, s90, 2
	s_add_u32 s46, s46, 0x100
	s_addc_u32 s47, s47, 0
	s_add_u32 s88, s88, 0x100
	s_addc_u32 s89, s89, 0
	s_cmp_gt_u32 s90, 29
	s_cbranch_scc0 .LBB0_920
	s_and_b64 vcc, exec, s[18:19]
	s_cbranch_vccz .LBB0_923
	s_barrier
